# attention loop: one LDS wait per two MFMAs; straight-line fast path across the tile barriers in skip mode
# speedup vs baseline: 1.0072x; 1.0016x over previous
.Lattn_A_fast:
	s_lshl_b32 s80, s10, 14
	v_add_u32_e32 v179, s80, v219
	v_add_u32_e32 v126, v179, v149
	ds_read_b128 v[102:105], v126 offset:49152
	ds_read_b128 v[118:121], v126 offset:53248
	ds_read_b128 v[122:125], v126 offset:57344
	ds_read_b128 v[228:231], v126 offset:61440
	s_add_i32 s78, s34, -1
	s_add_i32 s63, s60, 0x80
	s_lshl_b32 s79, s62, 14
	s_cmp_le_i32 s78, s48
	s_cselect_b64 s[4:5], -1, 0
	s_cmp_gt_i32 s78, s48
	s_waitcnt lgkmcnt(2)
	v_mfma_f32_32x32x16_bf16 v[50:65], v[102:105], v[98:101], v[50:65]
	v_exp_f32_e32 v66, v66
	v_exp_f32_e32 v249, v82
	v_add_u32_e32 v181, v179, v208
	ds_read_b128 v[102:105], v181 offset:49152
	v_mfma_f32_32x32x16_bf16 v[34:49], v[118:121], v[98:101], v[34:49]
	v_add_f32_e32 v254, 0, v66
	v_add_f32_e32 v254, v249, v254
	v_exp_f32_e32 v67, v67
	v_exp_f32_e32 v250, v83
	ds_read_b128 v[232:235], v181 offset:53248
	s_waitcnt lgkmcnt(2)
	v_mfma_f32_32x32x16_bf16 v[18:33], v[122:125], v[98:101], v[18:33]
	v_add_f32_e32 v254, v67, v254
	v_add_f32_e32 v254, v250, v254
	v_exp_f32_e32 v68, v68
	v_exp_f32_e32 v195, v84
	ds_read_b128 v[126:129], v181 offset:57344
	v_mfma_f32_32x32x16_bf16 v[2:17], v[228:231], v[98:101], v[2:17]
	v_add_f32_e32 v254, v68, v254
	v_add_f32_e32 v254, v195, v254
	v_exp_f32_e32 v69, v69
	v_exp_f32_e32 v251, v85
	ds_read_b128 v[118:121], v181 offset:61440
	s_waitcnt lgkmcnt(2)
	v_mfma_f32_32x32x16_bf16 v[50:65], v[102:105], v[106:109], v[50:65]
	v_add_f32_e32 v254, v69, v254
	v_add_f32_e32 v254, v251, v254
	v_exp_f32_e32 v70, v70
	v_exp_f32_e32 v252, v86
	v_add_u32_e32 v181, v179, v209
	ds_read_b128 v[122:125], v181 offset:49152
	v_mfma_f32_32x32x16_bf16 v[34:49], v[232:235], v[106:109], v[34:49]
	s_cbranch_scc1 .LBB0_458
	s_add_i32 s78, s34, -3
	s_add_i32 s81, s60, 0x100
	s_cmp_lt_i32 s78, s39
	s_cselect_b32 s82, s63, s81
	s_ashr_i32 s83, s82, 31
	s_lshl_b64 s[82:83], s[82:83], 12
	s_add_i32 s78, s79, 0xffffc000
	s_cmp_lg_u32 s62, 0
	s_cselect_b32 s78, s78, 0x8000
	v_lshl_add_u64 v[98:99], v[202:203], 0, s[82:83]
	s_add_i32 s78, s7, s78
	v_lshl_add_u64 v[100:101], v[98:99], 0, s[30:31]
	s_mov_b32 m0, s78
	v_lshl_add_u64 v[98:99], v[98:99], 0, s[36:37]
	global_load_lds_dwordx4 v[100:101], off
	s_add_i32 m0, s78, 0x2000
	s_nop 0
	global_load_lds_dwordx4 v[98:99], off
.LBB0_458:
	s_add_i32 s78, s34, -4
	s_cmp_gt_i32 s78, s39
	s_cselect_b64 s[82:83], -1, 0
	v_cndmask_b32_e64 v200, v201, -v201, s[82:83]
	s_and_b64 s[82:83], s[82:83], exec
	s_cselect_b32 s82, s63, s60
	s_ashr_i32 s83, s82, 31
	s_lshl_b64 s[84:85], s[82:83], 1
	s_addk_i32 s80, 0xc000
	s_cmp_lg_u32 s10, 0
	s_cselect_b32 s80, s80, 0x8000
	s_add_i32 s80, s14, s80
	v_lshl_add_u64 v[98:99], v[204:205], 0, s[84:85]
	s_add_i32 m0, s80, 0xc000
	v_lshl_add_u64 v[100:101], v[206:207], 0, s[84:85]
	global_load_lds_dwordx4 v[98:99], off
	s_add_i32 m0, s80, 0xc400
	v_cvt_f32_i32_e32 v98, s82
	global_load_lds_dwordx4 v[100:101], off
	v_add_u32_e32 v183, s79, v218
	v_add_f32_e32 v98, v155, v98
	v_fma_f32 v224, v200, v98, -v199
	v_fma_f32 v98, 0, v200, v224
	v_add_f32_e32 v99, v200, v224
	v_fma_f32 v100, v200, s64, v224
	v_fma_f32 v101, v200, s65, v224
	v_fma_f32 v102, v200, s66, v224
	v_fma_f32 v103, v200, s67, v224
	v_mul_f32_e32 v240, 0x42000000, v200
	ds_read_b128 v[228:231], v181 offset:53248
	s_waitcnt lgkmcnt(2)
	v_mfma_f32_32x32x16_bf16 v[18:33], v[126:129], v[106:109], v[18:33]
	v_add_f32_e32 v254, v70, v254
	v_add_f32_e32 v254, v252, v254
	v_exp_f32_e32 v71, v71
	v_fma_f32 v104, v200, s68, v224
	v_fma_f32 v105, v200, s69, v224
	ds_read_b128 v[126:129], v181 offset:57344
	v_mfma_f32_32x32x16_bf16 v[2:17], v[118:121], v[106:109], v[2:17]
	s_setprio 0
	v_add_f32_e32 v254, v71, v254
	v_exp_f32_e32 v253, v87
	v_exp_f32_e32 v82, v72
	ds_read_b128 v[118:121], v181 offset:61440
	s_waitcnt lgkmcnt(2)
	v_mfma_f32_32x32x16_bf16 v[50:65], v[122:125], v[110:113], v[50:65]
	v_add_f32_e32 v254, v253, v254
	v_add_f32_e32 v254, v82, v254
	v_exp_f32_e32 v72, v88
	v_fma_f32 v106, v200, s70, v224
	v_fma_f32 v107, v200, s71, v224
	v_add_u32_e32 v179, v179, v226
	ds_read_b128 v[122:125], v179 offset:49152
	v_mfma_f32_32x32x16_bf16 v[34:49], v[228:231], v[110:113], v[34:49]
	v_add_f32_e32 v254, v72, v254
	v_exp_f32_e32 v83, v73
	v_exp_f32_e32 v73, v89
	ds_read_b128 v[228:231], v179 offset:53248
	s_waitcnt lgkmcnt(2)
	v_mfma_f32_32x32x16_bf16 v[18:33], v[126:129], v[110:113], v[18:33]
	v_add_f32_e32 v254, v83, v254
	v_add_f32_e32 v254, v73, v254
	v_exp_f32_e32 v74, v74
	v_fma_f32 v108, v200, s72, v224
	v_fma_f32 v109, v200, s73, v224
	ds_read_b128 v[126:129], v179 offset:57344
	v_mfma_f32_32x32x16_bf16 v[2:17], v[118:121], v[110:113], v[2:17]
	v_add_f32_e32 v254, v74, v254
	v_exp_f32_e32 v90, v90
	v_exp_f32_e32 v75, v75
	ds_read_b128 v[118:121], v179 offset:61440
	s_waitcnt lgkmcnt(2)
	v_mfma_f32_32x32x16_bf16 v[50:65], v[122:125], v[114:117], v[50:65]
	v_add_f32_e32 v254, v90, v254
	v_add_f32_e32 v254, v75, v254
	v_exp_f32_e32 v91, v91
	v_fma_f32 v110, v200, s74, v224
	v_fma_f32 v111, v200, s75, v224
	v_add_u32_e32 v112, v183, v149
	ds_read_b128 v[232:235], v112
	v_mfma_f32_32x32x16_bf16 v[34:49], v[228:231], v[114:117], v[34:49]
	v_add_f32_e32 v254, v91, v254
	v_exp_f32_e32 v76, v76
	v_exp_f32_e32 v92, v92
	ds_read_b128 v[228:231], v112 offset:4096
	s_waitcnt lgkmcnt(2)
	v_mfma_f32_32x32x16_bf16 v[18:33], v[126:129], v[114:117], v[18:33]
	v_add_f32_e32 v254, v76, v254
	v_add_f32_e32 v254, v92, v254
	v_exp_f32_e32 v77, v77
	v_fma_f32 v112, v200, s76, v224
	v_fma_f32 v113, v200, s77, v224
	v_add_u32_e32 v179, v183, v208
	ds_read_b128 v[236:239], v179
	v_mfma_f32_32x32x16_bf16 v[2:17], v[118:121], v[114:117], v[2:17]
	v_add_f32_e64 v114, v240, v98
	v_add_f32_e64 v115, v240, v99
	v_add_f32_e64 v128, v240, v112
	v_add_f32_e64 v129, v240, v113
	v_add_f32_e64 v126, v240, v110
	v_add_f32_e64 v127, v240, v111
	v_add_f32_e32 v124, v240, v108
	v_add_f32_e32 v125, v240, v109
	v_add_f32_e32 v122, v240, v106
	v_add_f32_e32 v123, v240, v107
	v_add_f32_e32 v120, v240, v104
	v_add_f32_e32 v121, v240, v105
	v_add_f32_e32 v118, v240, v102
	v_add_f32_e32 v119, v240, v103
	v_add_f32_e32 v116, v240, v100
	v_add_f32_e32 v117, v240, v101
	ds_read_b128 v[240:243], v179 offset:4096
	s_waitcnt lgkmcnt(2)
	v_mfma_f32_32x32x16_bf16 v[98:113], v[232:235], v[130:133], v[98:113]
	v_add_f32_e32 v254, v77, v254
	v_exp_f32_e32 v93, v93
	v_exp_f32_e32 v78, v78
	v_add_u32_e32 v179, v183, v209
	ds_read_b128 v[232:235], v179
	v_mfma_f32_32x32x16_bf16 v[114:129], v[228:231], v[130:133], v[114:129]
	v_add_f32_e32 v254, v93, v254
	v_add_f32_e32 v254, v78, v254
	v_exp_f32_e32 v94, v94
	v_exp_f32_e32 v79, v79
	ds_read_b128 v[228:231], v179 offset:4096
	s_waitcnt lgkmcnt(2)
	v_mfma_f32_32x32x16_bf16 v[98:113], v[236:239], v[134:137], v[98:113]
	v_add_f32_e32 v254, v94, v254
	v_add_f32_e32 v254, v79, v254
	v_exp_f32_e32 v95, v95
	v_exp_f32_e32 v80, v80
	v_add_u32_e32 v179, v183, v226
	ds_read_b128 v[236:239], v179
	v_mfma_f32_32x32x16_bf16 v[114:129], v[240:243], v[134:137], v[114:129]
	v_add_f32_e32 v254, v95, v254
	v_add_f32_e32 v254, v80, v254
	v_exp_f32_e32 v96, v96
	v_exp_f32_e32 v81, v81
	ds_read_b128 v[240:243], v179 offset:4096
	s_waitcnt lgkmcnt(2)
	v_mfma_f32_32x32x16_bf16 v[98:113], v[232:235], v[138:141], v[98:113]
	v_add_f32_e32 v254, v96, v254
	v_add_f32_e32 v254, v81, v254
	v_exp_f32_e32 v97, v97
	v_mfma_f32_32x32x16_bf16 v[114:129], v[228:231], v[138:141], v[114:129]
	v_add_f32_e32 v254, v97, v254
	s_waitcnt lgkmcnt(0)
	v_mfma_f32_32x32x16_bf16 v[98:113], v[236:239], v[142:145], v[98:113]
	v_mfma_f32_32x32x16_bf16 v[114:129], v[240:243], v[142:145], v[114:129]
	s_cmp_lg_u32 s4, 0
	s_cbranch_scc0 .LBB0_471
	s_waitcnt vmcnt(4) lgkmcnt(0)
	s_barrier
	s_cmp_eq_u32 s100, 0
	s_cbranch_scc1 .Lattn_fair_a
	s_setprio 1
.Lattn_fair_a:
	s_andn2_b32 s4, s99, s2
	s_cbranch_scc0 .LBB0_460
	v_add_f32_e32 v179, v198, v254
	s_branch .LBB0_464

.Lattn_fair_0:
	s_cmp_lg_u32 s99, 0
	s_cbranch_scc1 .Lattn_A_fast
	s_branch .LBB0_452

.LBB0_471:
	s_mov_b64 s[4:5], -1
	s_waitcnt vmcnt(2) lgkmcnt(0)
	s_barrier
	s_cmp_eq_u32 s100, 0
	s_cbranch_scc1 .Lattn_fair_3
	s_setprio 1
